# v43 plus small exact edits: attention K/V staging writes issued before the last PV MFMAs, scalar tile-offset increment, no +0 adds; gla_pre grouped loads; 64-bit acc zero-init
# speedup vs baseline: 1.0067x; 1.0067x over previous
; #define LAS __attribute__((address_space(3)))
; __device__ __forceinline__ unsigned cvtpk(float lo, float hi) { return pg8::cvt_pk_bf16(lo, hi); }
; __device__ __forceinline__ float bflo(unsigned u) { return __uint_as_float(u << 16); }
; __device__ __forceinline__ float bfhi(unsigned u) { return __uint_as_float(u & 0xffff0000u); }
; __device__ __forceinline__ void attn_phase(LAS unsigned char* lds, const bf16_t* proj, bf16_t* oa, const float* lamp, const float* subg, const float* relb, const float* qg, int wg, int tid) {
;     ...
;         const int qb = (ui == 0) ? sx : (ui == 1) ? 15 - sx : (ui == 2) ? 16 + sx : 31 - sx;
;         const int q0 = qb * 128, qw0 = q0 + wave * 16, nkt = (q0 + 128) / 32;
;         LAS bf16_t* Qw = Qs + wave * (2 * 16 * KP);
; #pragma unroll
;         for (int s = 0; s < 2; ++s) { u32x4 qc[4]; float ss = 0.f;
; #pragma unroll
;             for (int ks = 0; ks < 4; ++ks) { qc[ks] = *(const u32x4*)(proj + (rb + qw0 + fr) * DIFF_IN + (2 * h + s) * 128 + 32 * ks + 8 * fq);
; #pragma unroll
;                 for (int e = 0; e < 4; ++e) { const float a = bflo(qc[ks][e]), c = bfhi(qc[ks][e]); ss += a * a + c * c; } }
;             ss += __shfl_xor(ss, 16); ss += __shfl_xor(ss, 32);
;             const float rs = (1.0f / sqrtf(ss * (1.f / 128.f) + EPS)) * QSCALE;
; #pragma unroll
;             for (int ks = 0; ks < 4; ++ks) { const f32x4 g0 = *(const f32x4*)(qg + 32 * ks + 8 * fq), g1 = *(const f32x4*)(qg + 32 * ks + 8 * fq + 4);
;                 u32x4 o; o.x = cvtpk(bflo(qc[ks].x) * rs * g0[0], bfhi(qc[ks].x) * rs * g0[1]); o.y = cvtpk(bflo(qc[ks].y) * rs * g0[2], bfhi(qc[ks].y) * rs * g0[3]);
;                 o.z = cvtpk(bflo(qc[ks].z) * rs * g1[0], bfhi(qc[ks].z) * rs * g1[1]); o.w = cvtpk(bflo(qc[ks].w) * rs * g1[2], bfhi(qc[ks].w) * rs * g1[3]);
;                 *(LAS u32x4*)(Qw + (s * 16 + fr) * KP + 32 * ks + 8 * fq) = o; } }
.LBB0_593:
	s_lshl_b32 s0, s20, 7
	s_add_i32 s40, s0, s6
	s_ashr_i32 s41, s40, 31
	v_lshl_add_u64 v[18:19], v[168:169], 0, s[40:41]
	v_mad_u64_u32 v[58:59], s[20:21], v18, s28, v[200:201]
	v_mov_b32_e32 v0, v59
	v_mad_u64_u32 v[18:19], s[20:21], v19, s28, v[0:1]
	v_mov_b32_e32 v59, v18
	global_load_dwordx4 v[38:41], v[58:59], off offset:192
	global_load_dwordx4 v[42:45], v[58:59], off
	global_load_dwordx4 v[46:49], v[58:59], off offset:64
	global_load_dwordx4 v[84:87], v[58:59], off offset:128
	global_load_dwordx4 v[18:21], v[170:171], off offset:16
	global_load_dwordx4 v[22:25], v[170:171], off
	global_load_dwordx4 v[26:29], v[170:171], off offset:144
	global_load_dwordx4 v[30:33], v[170:171], off offset:128
	global_load_dwordx4 v[34:37], v[170:171], off offset:256
	s_add_i32 s20, s0, 0x80
	s_mov_b32 s33, 1
	s_lshr_b32 s34, s20, 5
	s_or_b32 s35, s40, 15
	s_sub_i32 s36, s40, 31
	s_mov_b32 s37, 0
	s_mov_b64 s[100:101], s[72:73]
	v_mov_b64_e32 v[210:211], v[208:209]
	v_mov_b64_e32 v[212:213], v[206:207]
	v_mov_b64_e32 v[214:215], v[204:205]
	v_mov_b64_e32 v[216:217], v[202:203]
	s_waitcnt vmcnt(8)
	v_and_b32_e32 v57, 0xffff0000, v39
	s_waitcnt vmcnt(7)
	v_lshlrev_b32_e32 v76, 16, v45
	v_and_b32_e32 v77, 0xffff0000, v45
	v_lshlrev_b32_e32 v80, 16, v43
	v_and_b32_e32 v81, 0xffff0000, v43
	v_lshlrev_b32_e32 v82, 16, v42
	v_and_b32_e32 v83, 0xffff0000, v42
	v_lshlrev_b32_e32 v78, 16, v44
	v_and_b32_e32 v79, 0xffff0000, v44
	s_waitcnt vmcnt(6)
	v_lshlrev_b32_e32 v64, 16, v49
	v_and_b32_e32 v65, 0xffff0000, v49
	v_lshlrev_b32_e32 v68, 16, v48
	v_and_b32_e32 v69, 0xffff0000, v48
	v_lshlrev_b32_e32 v72, 16, v47
	v_and_b32_e32 v73, 0xffff0000, v47
	v_lshlrev_b32_e32 v74, 16, v46
	v_and_b32_e32 v75, 0xffff0000, v46
	v_pk_mul_f32 v[42:43], v[76:77], v[76:77]
	v_pk_mul_f32 v[46:47], v[80:81], v[80:81]
	v_pk_mul_f32 v[48:49], v[82:83], v[82:83]
	v_pk_mul_f32 v[44:45], v[78:79], v[78:79]
	v_add_f32_e32 v0, v42, v43
	v_add_f32_e32 v42, v46, v47
	v_add_f32_e32 v43, v48, v49
	v_add_f32_e32 v44, v44, v45
	v_add_f32_e32 v42, v43, v42
	v_pk_mul_f32 v[90:91], v[74:75], v[74:75]
	v_add_f32_e32 v42, v44, v42
	v_pk_mul_f32 v[88:89], v[72:73], v[72:73]
	v_add_f32_e32 v45, v90, v91
	v_add_f32_e32 v0, v0, v42
	s_waitcnt vmcnt(5)
	v_lshlrev_b32_e32 v60, 16, v87
	v_and_b32_e32 v61, 0xffff0000, v87
	v_lshlrev_b32_e32 v62, 16, v86
	v_and_b32_e32 v63, 0xffff0000, v86
	v_pk_mul_f32 v[86:87], v[68:69], v[68:69]
	v_add_f32_e32 v46, v88, v89
	v_add_f32_e32 v0, v45, v0
	v_lshlrev_b32_e32 v66, 16, v85
	v_and_b32_e32 v67, 0xffff0000, v85
	v_lshlrev_b32_e32 v70, 16, v84
	v_and_b32_e32 v71, 0xffff0000, v84
	v_pk_mul_f32 v[84:85], v[64:65], v[64:65]
	v_add_f32_e32 v47, v86, v87
	v_add_f32_e32 v0, v46, v0
	v_pk_mul_f32 v[98:99], v[70:71], v[70:71]
	v_add_f32_e32 v48, v84, v85
	v_add_f32_e32 v0, v47, v0
	v_pk_mul_f32 v[96:97], v[66:67], v[66:67]
	v_add_f32_e32 v49, v98, v99
	v_add_f32_e32 v0, v48, v0
	v_pk_mul_f32 v[94:95], v[62:63], v[62:63]
	v_add_f32_e32 v84, v96, v97
	v_add_f32_e32 v0, v49, v0
	v_and_b32_e32 v56, 0xffff0000, v38
	v_pk_mul_f32 v[92:93], v[60:61], v[60:61]
	v_add_f32_e32 v85, v94, v95
	v_add_f32_e32 v0, v84, v0
	v_lshlrev_b32_e32 v55, 16, v39
	v_lshlrev_b32_e32 v54, 16, v38
	v_pk_mul_f32 v[38:39], v[56:57], v[56:57]
	v_add_f32_e32 v86, v92, v93
	v_add_f32_e32 v0, v85, v0
	v_and_b32_e32 v53, 0xffff0000, v41
	v_and_b32_e32 v52, 0xffff0000, v40
	v_pk_fma_f32 v[38:39], v[54:55], v[54:55], v[38:39]
	v_add_f32_e32 v0, v86, v0
	v_lshlrev_b32_e32 v51, 16, v41
	v_lshlrev_b32_e32 v50, 16, v40
	v_pk_mul_f32 v[40:41], v[52:53], v[52:53]
	v_add_f32_e32 v0, v38, v0
	v_pk_fma_f32 v[40:41], v[50:51], v[50:51], v[40:41]
	v_add_f32_e32 v0, v39, v0
	v_add_f32_e32 v0, v40, v0
	v_add_f32_e32 v0, v41, v0
	ds_bpermute_b32 v42, v232, v0
	global_load_dwordx4 v[38:41], v[170:171], off offset:272
	s_waitcnt lgkmcnt(0)
	v_add_f32_e32 v0, v0, v42
	ds_bpermute_b32 v92, v233, v0
	global_load_dwordx4 v[42:45], v[170:171], off offset:400
	global_load_dwordx4 v[46:49], v[170:171], off offset:384
	global_load_dwordx4 v[84:87], v[58:59], off offset:384
	global_load_dwordx4 v[88:91], v[58:59], off offset:448
	s_waitcnt lgkmcnt(0)
	v_add_f32_e32 v0, v0, v92
	v_fmamk_f32 v0, v0, 0x3c000000, v189
	v_mul_f32_e32 v92, 0x4f800000, v0
	v_cmp_gt_f32_e32 vcc, s22, v0
	s_waitcnt vmcnt(1)
; #define LAS __attribute__((address_space(3)))
; __device__ __forceinline__ unsigned cvtpk(float lo, float hi) { return pg8::cvt_pk_bf16(lo, hi); }
; __device__ __forceinline__ float bflo(unsigned u) { return __uint_as_float(u << 16); }
; __device__ __forceinline__ float bfhi(unsigned u) { return __uint_as_float(u & 0xffff0000u); }
; __device__ __forceinline__ void attn_phase(LAS unsigned char* lds, const bf16_t* proj, bf16_t* oa, const float* lamp, const float* subg, const float* relb, const float* qg, int wg, int tid) {
;     ...
;         for (int s = 0; s < 2; ++s) { u32x4 qc[4]; float ss = 0.f;
; #pragma unroll
;             for (int ks = 0; ks < 4; ++ks) { qc[ks] = *(const u32x4*)(proj + (rb + qw0 + fr) * DIFF_IN + (2 * h + s) * 128 + 32 * ks + 8 * fq);
; #pragma unroll
;                 for (int e = 0; e < 4; ++e) { const float a = bflo(qc[ks][e]), c = bfhi(qc[ks][e]); ss += a * a + c * c; } }
;             ss += __shfl_xor(ss, 16); ss += __shfl_xor(ss, 32);
;             const float rs = (1.0f / sqrtf(ss * (1.f / 128.f) + EPS)) * QSCALE;
; #pragma unroll
;             for (int ks = 0; ks < 4; ++ks) { const f32x4 g0 = *(const f32x4*)(qg + 32 * ks + 8 * fq), g1 = *(const f32x4*)(qg + 32 * ks + 8 * fq + 4);
;                 u32x4 o; o.x = cvtpk(bflo(qc[ks].x) * rs * g0[0], bfhi(qc[ks].x) * rs * g0[1]); o.y = cvtpk(bflo(qc[ks].y) * rs * g0[2], bfhi(qc[ks].y) * rs * g0[3]);
;                 o.z = cvtpk(bflo(qc[ks].z) * rs * g1[0], bfhi(qc[ks].z) * rs * g1[1]); o.w = cvtpk(bflo(qc[ks].w) * rs * g1[2], bfhi(qc[ks].w) * rs * g1[3]);
;                 *(LAS u32x4*)(Qw + (s * 16 + fr) * KP + 32 * ks + 8 * fq) = o; } }
	v_lshlrev_b32_e32 v116, 16, v84
	v_cndmask_b32_e32 v0, v0, v92, vcc
	v_sqrt_f32_e32 v96, v0
	global_load_dwordx4 v[92:95], v[58:59], off offset:256
	v_and_b32_e32 v117, 0xffff0000, v84
	v_lshlrev_b32_e32 v112, 16, v85
	v_add_u32_e32 v97, -1, v96
	v_add_u32_e32 v98, 1, v96
	v_fma_f32 v99, -v97, v96, v0
	v_fma_f32 v100, -v98, v96, v0
	v_cmp_ge_f32_e64 s[0:1], 0, v99
	v_and_b32_e32 v113, 0xffff0000, v85
	v_pk_mul_f32 v[84:85], v[116:117], v[116:117]
	v_cndmask_b32_e64 v96, v96, v97, s[0:1]
	v_cmp_lt_f32_e64 s[0:1], 0, v100
	v_lshlrev_b32_e32 v110, 16, v86
	v_and_b32_e32 v111, 0xffff0000, v86
	v_cndmask_b32_e64 v96, v96, v98, s[0:1]
	v_mul_f32_e32 v97, 0x37800000, v96
	v_cndmask_b32_e32 v96, v96, v97, vcc
	v_cmp_class_f32_e32 vcc, v0, v191
	v_pk_mul_f32 v[114:115], v[112:113], v[112:113]
	v_lshlrev_b32_e32 v106, 16, v87
	v_cndmask_b32_e32 v0, v96, v0, vcc
	global_load_dwordx4 v[96:99], v[58:59], off offset:320
	v_div_scale_f32 v100, s[0:1], v0, v0, 1.0
	v_rcp_f32_e32 v101, v100
	v_div_scale_f32 v58, vcc, 1.0, v0, 1.0
	v_and_b32_e32 v107, 0xffff0000, v87
	v_fma_f32 v59, -v100, v101, 1.0
	v_fmac_f32_e32 v101, v59, v101
	v_mul_f32_e32 v59, v58, v101
	v_fma_f32 v102, -v100, v59, v58
	v_fmac_f32_e32 v59, v102, v101
	v_fma_f32 v58, -v100, v59, v58
	v_div_fmas_f32 v58, v58, v101, v59
	v_div_fixup_f32 v0, v58, v0, 1.0
	v_mul_f32_e32 v0, 0x3e0293ee, v0
	v_pk_mul_f32 v[58:59], v[0:1], v[82:83] op_sel_hi:[0,1]
	v_pk_mul_f32 v[78:79], v[0:1], v[78:79] op_sel_hi:[0,1]
	v_pk_mul_f32 v[82:83], v[0:1], v[76:77] op_sel_hi:[0,1]
	v_pk_mul_f32 v[58:59], v[22:23], v[58:59]
	v_pk_mul_f32 v[78:79], v[18:19], v[78:79]
	v_cvt_pk_bf16_f32 v76, v58, v59
	v_pk_mul_f32 v[58:59], v[20:21], v[82:83]
	v_cvt_pk_bf16_f32 v78, v78, v79
	v_cvt_pk_bf16_f32 v79, v58, v59
	v_pk_mul_f32 v[58:59], v[0:1], v[74:75] op_sel_hi:[0,1]
	v_pk_mul_f32 v[58:59], v[30:31], v[58:59]
	v_pk_mul_f32 v[80:81], v[0:1], v[80:81] op_sel_hi:[0,1]
	v_cvt_pk_bf16_f32 v74, v58, v59
	v_pk_mul_f32 v[58:59], v[0:1], v[72:73] op_sel_hi:[0,1]
	v_pk_mul_f32 v[58:59], v[32:33], v[58:59]
	v_pk_mul_f32 v[80:81], v[24:25], v[80:81]
	v_cvt_pk_bf16_f32 v75, v58, v59
	v_pk_mul_f32 v[58:59], v[0:1], v[68:69] op_sel_hi:[0,1]
	v_cvt_pk_bf16_f32 v77, v80, v81
	v_pk_mul_f32 v[58:59], v[26:27], v[58:59]
	ds_write_b128 v248, v[76:79]
	v_cvt_pk_bf16_f32 v76, v58, v59
	v_pk_mul_f32 v[58:59], v[0:1], v[64:65] op_sel_hi:[0,1]
	v_pk_mul_f32 v[58:59], v[28:29], v[58:59]
	v_pk_mul_f32 v[86:87], v[110:111], v[110:111]
	v_cvt_pk_bf16_f32 v77, v58, v59
	v_pk_mul_f32 v[58:59], v[0:1], v[70:71] op_sel_hi:[0,1]
	v_pk_mul_f32 v[58:59], v[34:35], v[58:59]
	ds_write_b128 v248, v[74:77] offset:64
	v_cvt_pk_bf16_f32 v64, v58, v59
	v_pk_mul_f32 v[58:59], v[0:1], v[66:67] op_sel_hi:[0,1]
	v_pk_mul_f32 v[58:59], v[36:37], v[58:59]
	v_pk_mul_f32 v[108:109], v[106:107], v[106:107]
	v_cvt_pk_bf16_f32 v65, v58, v59
	v_pk_mul_f32 v[58:59], v[0:1], v[62:63] op_sel_hi:[0,1]
	v_pk_mul_f32 v[58:59], v[38:39], v[58:59]
	s_waitcnt vmcnt(2)
	v_and_b32_e32 v63, 0xffff0000, v89
	v_cvt_pk_bf16_f32 v66, v58, v59
	v_pk_mul_f32 v[58:59], v[0:1], v[60:61] op_sel_hi:[0,1]
	v_pk_mul_f32 v[58:59], v[40:41], v[58:59]
	v_and_b32_e32 v62, 0xffff0000, v88
	v_cvt_pk_bf16_f32 v67, v58, v59
	v_mov_b32_e32 v58, v54
	v_mov_b32_e32 v59, v56
	v_pk_mul_f32 v[58:59], v[0:1], v[58:59] op_sel_hi:[0,1]
	v_pk_mul_f32 v[58:59], v[46:47], v[58:59]
	s_waitcnt vmcnt(1)
	v_lshlrev_b32_e32 v78, 16, v95
	v_cvt_pk_bf16_f32 v54, v58, v59
	v_lshlrev_b32_e32 v59, 16, v89
	v_lshlrev_b32_e32 v58, 16, v88
	v_and_b32_e32 v79, 0xffff0000, v95
	v_lshlrev_b32_e32 v82, 16, v93
	v_and_b32_e32 v83, 0xffff0000, v93
	v_lshlrev_b32_e32 v88, 16, v92
	v_and_b32_e32 v89, 0xffff0000, v92
	v_pk_mul_f32 v[70:71], v[78:79], v[78:79]
	v_lshlrev_b32_e32 v80, 16, v94
	v_and_b32_e32 v81, 0xffff0000, v94
	v_pk_mul_f32 v[74:75], v[82:83], v[82:83]
	v_pk_mul_f32 v[76:77], v[88:89], v[88:89]
	v_pk_mul_f32 v[72:73], v[80:81], v[80:81]
	v_add_f32_e32 v56, v70, v71
	v_add_f32_e32 v70, v74, v75
	v_add_f32_e32 v71, v76, v77
	s_waitcnt vmcnt(0)
	v_lshlrev_b32_e32 v104, 16, v96
	v_and_b32_e32 v105, 0xffff0000, v96
	v_add_f32_e32 v70, v71, v70
	v_add_f32_e32 v71, v72, v73
	v_lshlrev_b32_e32 v100, 16, v97
	v_and_b32_e32 v101, 0xffff0000, v97
	v_pk_mul_f32 v[96:97], v[104:105], v[104:105]
	v_add_f32_e32 v70, v71, v70
	v_pk_mul_f32 v[60:61], v[62:63], v[62:63]
	v_lshlrev_b32_e32 v94, 16, v98
	v_and_b32_e32 v95, 0xffff0000, v98
	v_pk_mul_f32 v[102:103], v[100:101], v[100:101]
	v_add_f32_e32 v56, v56, v70
	v_add_f32_e32 v70, v96, v97
	ds_write_b128 v248, v[64:67] offset:128
	v_pk_fma_f32 v[66:67], v[58:59], v[58:59], v[60:61]
	v_lshlrev_b32_e32 v61, 16, v91
	v_lshlrev_b32_e32 v60, 16, v90
	v_and_b32_e32 v65, 0xffff0000, v91
	v_and_b32_e32 v64, 0xffff0000, v90
	v_lshlrev_b32_e32 v90, 16, v99
	v_and_b32_e32 v91, 0xffff0000, v99
	v_pk_mul_f32 v[98:99], v[94:95], v[94:95]
	v_add_f32_e32 v56, v70, v56
	v_add_f32_e32 v70, v102, v103
	v_pk_mul_f32 v[92:93], v[90:91], v[90:91]
	v_add_f32_e32 v56, v70, v56
	v_add_f32_e32 v70, v98, v99
	v_add_f32_e32 v56, v70, v56
	v_add_f32_e32 v70, v92, v93
	v_add_f32_e32 v56, v70, v56
	v_add_f32_e32 v70, v84, v85
	v_add_f32_e32 v56, v70, v56
	v_add_f32_e32 v70, v114, v115
	v_add_f32_e32 v56, v70, v56
	v_add_f32_e32 v70, v86, v87
	v_add_f32_e32 v56, v70, v56
	v_add_f32_e32 v70, v108, v109
	v_add_f32_e32 v56, v70, v56
	v_pk_mul_f32 v[68:69], v[64:65], v[64:65]
	v_add_f32_e32 v56, v66, v56
	v_pk_fma_f32 v[68:69], v[60:61], v[60:61], v[68:69]
	v_add_f32_e32 v56, v67, v56
	v_add_f32_e32 v56, v68, v56
	v_add_f32_e32 v66, v69, v56
	ds_bpermute_b32 v67, v232, v66
	v_mov_b32_e32 v56, v55
	v_pk_mul_f32 v[56:57], v[0:1], v[56:57] op_sel_hi:[0,1]
	v_pk_mul_f32 v[56:57], v[48:49], v[56:57]
	s_waitcnt lgkmcnt(0)
; #define LAS __attribute__((address_space(3)))
; __device__ __forceinline__ unsigned cvtpk(float lo, float hi) { return pg8::cvt_pk_bf16(lo, hi); }
; __device__ __forceinline__ float bflo(unsigned u) { return __uint_as_float(u << 16); }
; __device__ __forceinline__ float bfhi(unsigned u) { return __uint_as_float(u & 0xffff0000u); }
; __device__ __forceinline__ void attn_phase(LAS unsigned char* lds, const bf16_t* proj, bf16_t* oa, const float* lamp, const float* subg, const float* relb, const float* qg, int wg, int tid) {
;     ...
;             ss += __shfl_xor(ss, 16); ss += __shfl_xor(ss, 32);
;             const float rs = (1.0f / sqrtf(ss * (1.f / 128.f) + EPS)) * QSCALE;
; #pragma unroll
;             for (int ks = 0; ks < 4; ++ks) { const f32x4 g0 = *(const f32x4*)(qg + 32 * ks + 8 * fq), g1 = *(const f32x4*)(qg + 32 * ks + 8 * fq + 4);
;                 u32x4 o; o.x = cvtpk(bflo(qc[ks].x) * rs * g0[0], bfhi(qc[ks].x) * rs * g0[1]); o.y = cvtpk(bflo(qc[ks].y) * rs * g0[2], bfhi(qc[ks].y) * rs * g0[3]);
;                 o.z = cvtpk(bflo(qc[ks].z) * rs * g1[0], bfhi(qc[ks].z) * rs * g1[1]); o.w = cvtpk(bflo(qc[ks].w) * rs * g1[2], bfhi(qc[ks].w) * rs * g1[3]);
;                 *(LAS u32x4*)(Qw + (s * 16 + fr) * KP + 32 * ks + 8 * fq) = o; } }
; #pragma unroll
;         for (int i = 0; i < 2; ++i) { const int id = tid + 512 * i, s = id >> 9, row = (id >> 4) & 31, ch = id & 15;
;             *(LAS u32x4*)(Kb + (s * 32 + row) * KP + ch * 8) = *(const u32x4*)(ksrc + (size_t)row * DIFF_IN + s * 128 + ch * 8); }
; #pragma unroll
;         for (int i = 0; i < 2; ++i) { const int id = tid + 512 * i, row = id >> 5, ch = id & 31;
;             *(LAS u32x4*)(Vb + row * VP + ch * 8) = *(const u32x4*)(vsrc + (size_t)row * DIFF_IN + ch * 8); }
;         __syncthreads();
;         float l0 = 0.f, l1 = 0.f;
;         f32x4 o[2][16];
; #pragma unroll
;         for (int s = 0; s < 2; ++s)
; #pragma unroll
;             for (int vt = 0; vt < 16; ++vt) o[s][vt] = (f32x4){0.f, 0.f, 0.f, 0.f};
	v_add_f32_e32 v66, v66, v67
	ds_bpermute_b32 v67, v233, v66
	v_cvt_pk_bf16_f32 v55, v56, v57
	v_mov_b32_e32 v56, v50
	v_mov_b32_e32 v57, v52
	v_pk_mul_f32 v[56:57], v[0:1], v[56:57] op_sel_hi:[0,1]
	s_waitcnt lgkmcnt(0)
	v_add_f32_e32 v50, v66, v67
	v_fmamk_f32 v50, v50, 0x3c000000, v189
	v_mul_f32_e32 v52, 0x4f800000, v50
	v_cmp_gt_f32_e32 vcc, s22, v50
	v_pk_mul_f32 v[56:57], v[42:43], v[56:57]
	s_nop 0
	v_cndmask_b32_e32 v50, v50, v52, vcc
	v_sqrt_f32_e32 v66, v50
	v_mov_b32_e32 v52, v51
	v_pk_mul_f32 v[84:85], v[0:1], v[52:53] op_sel_hi:[0,1]
	v_pk_mul_f32 v[84:85], v[44:45], v[84:85]
	v_add_u32_e32 v0, -1, v66
	v_fma_f32 v51, -v0, v66, v50
	v_cmp_ge_f32_e64 s[0:1], 0, v51
	v_add_u32_e32 v51, 1, v66
	v_fma_f32 v52, -v51, v66, v50
	v_cndmask_b32_e64 v0, v66, v0, s[0:1]
	v_cmp_lt_f32_e64 s[0:1], 0, v52
	v_cvt_pk_bf16_f32 v56, v56, v57
	v_cvt_pk_bf16_f32 v57, v84, v85
	v_cndmask_b32_e64 v0, v0, v51, s[0:1]
	v_mul_f32_e32 v51, 0x37800000, v0
	v_cndmask_b32_e32 v0, v0, v51, vcc
	v_cmp_class_f32_e32 vcc, v50, v191
	s_nop 1
	v_cndmask_b32_e32 v0, v0, v50, vcc
	global_load_dwordx4 v[50:53], v[178:179], off
	global_load_dwordx4 v[66:69], v[180:181], off
	global_load_dwordx4 v[70:73], v[182:183], off
	global_load_dwordx4 v[74:77], v[184:185], off
	v_div_scale_f32 v86, s[0:1], v0, v0, 1.0
	v_rcp_f32_e32 v87, v86
	ds_write_b128 v248, v[54:57] offset:192
	v_fma_f32 v54, -v86, v87, 1.0
	v_fmac_f32_e32 v87, v54, v87
	v_div_scale_f32 v54, vcc, 1.0, v0, 1.0
	v_mul_f32_e32 v55, v54, v87
	v_fma_f32 v56, -v86, v55, v54
	v_fmac_f32_e32 v55, v56, v87
	v_fma_f32 v54, -v86, v55, v54
	v_div_fmas_f32 v54, v54, v87, v55
	v_div_fixup_f32 v0, v54, v0, 1.0
	v_mul_f32_e32 v0, 0x3e0293ee, v0
	v_pk_mul_f32 v[54:55], v[0:1], v[88:89] op_sel_hi:[0,1]
	v_pk_mul_f32 v[22:23], v[22:23], v[54:55]
	v_pk_mul_f32 v[54:55], v[0:1], v[82:83] op_sel_hi:[0,1]
	v_pk_mul_f32 v[24:25], v[24:25], v[54:55]
	v_cvt_pk_bf16_f32 v22, v22, v23
	v_cvt_pk_bf16_f32 v23, v24, v25
	v_pk_mul_f32 v[24:25], v[0:1], v[80:81] op_sel_hi:[0,1]
	v_pk_mul_f32 v[18:19], v[18:19], v[24:25]
	s_nop 0
	v_cvt_pk_bf16_f32 v24, v18, v19
	v_pk_mul_f32 v[18:19], v[0:1], v[78:79] op_sel_hi:[0,1]
	v_pk_mul_f32 v[18:19], v[20:21], v[18:19]
	v_pk_mul_f32 v[20:21], v[0:1], v[100:101] op_sel_hi:[0,1]
	v_cvt_pk_bf16_f32 v25, v18, v19
	v_pk_mul_f32 v[18:19], v[0:1], v[104:105] op_sel_hi:[0,1]
	v_pk_mul_f32 v[18:19], v[30:31], v[18:19]
	v_pk_mul_f32 v[20:21], v[32:33], v[20:21]
	ds_write_b128 v248, v[22:25] offset:4608
	v_cvt_pk_bf16_f32 v18, v18, v19
	v_cvt_pk_bf16_f32 v19, v20, v21
	v_pk_mul_f32 v[20:21], v[0:1], v[94:95] op_sel_hi:[0,1]
	v_pk_mul_f32 v[22:23], v[0:1], v[90:91] op_sel_hi:[0,1]
	v_pk_mul_f32 v[20:21], v[26:27], v[20:21]
	v_pk_mul_f32 v[22:23], v[28:29], v[22:23]
	v_cvt_pk_bf16_f32 v20, v20, v21
	v_cvt_pk_bf16_f32 v21, v22, v23
	ds_write_b128 v248, v[18:21] offset:4672
	v_pk_mul_f32 v[18:19], v[0:1], v[116:117] op_sel_hi:[0,1]
	v_pk_mul_f32 v[20:21], v[0:1], v[112:113] op_sel_hi:[0,1]
	v_pk_mul_f32 v[18:19], v[34:35], v[18:19]
	v_pk_mul_f32 v[20:21], v[36:37], v[20:21]
	v_cvt_pk_bf16_f32 v18, v18, v19
	v_cvt_pk_bf16_f32 v19, v20, v21
	v_pk_mul_f32 v[20:21], v[0:1], v[110:111] op_sel_hi:[0,1]
	v_pk_mul_f32 v[22:23], v[0:1], v[106:107] op_sel_hi:[0,1]
	v_pk_mul_f32 v[20:21], v[38:39], v[20:21]
	v_pk_mul_f32 v[22:23], v[40:41], v[22:23]
	v_cvt_pk_bf16_f32 v20, v20, v21
	v_cvt_pk_bf16_f32 v21, v22, v23
	ds_write_b128 v248, v[18:21] offset:4736
	v_mov_b32_e32 v18, v58
	v_mov_b32_e32 v19, v62
	v_mov_b32_e32 v62, v59
	v_pk_mul_f32 v[18:19], v[0:1], v[18:19] op_sel_hi:[0,1]
	v_pk_mul_f32 v[20:21], v[0:1], v[62:63] op_sel_hi:[0,1]
	v_pk_mul_f32 v[18:19], v[46:47], v[18:19]
	v_pk_mul_f32 v[20:21], v[48:49], v[20:21]
	v_cvt_pk_bf16_f32 v18, v18, v19
	v_cvt_pk_bf16_f32 v19, v20, v21
	v_mov_b32_e32 v20, v60
	v_mov_b32_e32 v21, v64
	v_mov_b32_e32 v64, v61
	v_pk_mul_f32 v[20:21], v[0:1], v[20:21] op_sel_hi:[0,1]
	v_pk_mul_f32 v[22:23], v[0:1], v[64:65] op_sel_hi:[0,1]
	v_pk_mul_f32 v[20:21], v[42:43], v[20:21]
	v_pk_mul_f32 v[22:23], v[44:45], v[22:23]
	v_cvt_pk_bf16_f32 v20, v20, v21
	v_cvt_pk_bf16_f32 v21, v22, v23
	v_add_u32_e32 v0, v235, v237
	ds_write_b128 v248, v[18:21] offset:4800
	s_waitcnt vmcnt(3)
	ds_write_b128 v249, v[50:53]
	s_waitcnt vmcnt(2)
	ds_write_b128 v250, v[66:69]
	s_waitcnt vmcnt(1)
	ds_write_b128 v0, v[70:73] offset:36864
	v_add_u32_e32 v0, v235, v238
	v_mov_b32_e32 v20, v1
	v_mov_b32_e32 v21, v1
	s_waitcnt vmcnt(0)
	ds_write_b128 v0, v[74:77] offset:36864
	v_mov_b32_e32 v0, v1
	v_mov_b32_e32 v18, v1
	v_mov_b32_e32 v19, v1
	v_mov_b64_e32 v[24:25], v[20:21]
	v_mov_b64_e32 v[32:33], v[20:21]
	v_mov_b64_e32 v[44:45], v[20:21]
	v_mov_b64_e32 v[52:53], v[20:21]
	v_mov_b64_e32 v[60:61], v[20:21]
	v_mov_b64_e32 v[68:69], v[20:21]
	v_mov_b64_e32 v[76:77], v[20:21]
	v_mov_b64_e32 v[84:85], v[20:21]
	v_mov_b64_e32 v[92:93], v[20:21]
	v_mov_b64_e32 v[100:101], v[20:21]
	v_mov_b64_e32 v[108:109], v[20:21]
	v_mov_b64_e32 v[116:117], v[20:21]
	v_mov_b64_e32 v[124:125], v[20:21]
	v_mov_b64_e32 v[132:133], v[20:21]
	v_mov_b64_e32 v[140:141], v[20:21]
	v_mov_b64_e32 v[28:29], v[20:21]
	v_mov_b64_e32 v[36:37], v[20:21]
	v_mov_b64_e32 v[40:41], v[20:21]
	v_mov_b64_e32 v[48:49], v[20:21]
	v_mov_b64_e32 v[56:57], v[20:21]
	v_mov_b64_e32 v[64:65], v[20:21]
	v_mov_b64_e32 v[72:73], v[20:21]
	v_mov_b64_e32 v[80:81], v[20:21]
	v_mov_b64_e32 v[88:89], v[20:21]
	v_mov_b64_e32 v[96:97], v[20:21]
	v_mov_b64_e32 v[104:105], v[20:21]
	v_mov_b64_e32 v[112:113], v[20:21]
	v_mov_b64_e32 v[120:121], v[20:21]
	v_mov_b64_e32 v[128:129], v[20:21]
	v_mov_b64_e32 v[136:137], v[20:21]
	v_mov_b64_e32 v[144:145], v[20:21]
	v_mov_b64_e32 v[22:23], v[18:19]
	v_mov_b64_e32 v[30:31], v[18:19]
	v_mov_b64_e32 v[42:43], v[18:19]
	v_mov_b64_e32 v[50:51], v[18:19]
	v_mov_b64_e32 v[58:59], v[18:19]
	v_mov_b64_e32 v[66:67], v[18:19]
	v_mov_b64_e32 v[74:75], v[18:19]
	v_mov_b64_e32 v[82:83], v[18:19]
	v_mov_b64_e32 v[90:91], v[18:19]
	v_mov_b64_e32 v[98:99], v[18:19]
	v_mov_b64_e32 v[106:107], v[18:19]
	v_mov_b64_e32 v[114:115], v[18:19]
	v_mov_b64_e32 v[122:123], v[18:19]
	v_mov_b64_e32 v[130:131], v[18:19]
	v_mov_b64_e32 v[138:139], v[18:19]
	v_mov_b64_e32 v[26:27], v[18:19]
	v_mov_b64_e32 v[34:35], v[18:19]
	v_mov_b64_e32 v[38:39], v[18:19]
	v_mov_b64_e32 v[46:47], v[18:19]
	v_mov_b64_e32 v[54:55], v[18:19]
	v_mov_b64_e32 v[62:63], v[18:19]
	v_mov_b64_e32 v[70:71], v[18:19]
	v_mov_b64_e32 v[78:79], v[18:19]
	v_mov_b64_e32 v[86:87], v[18:19]
	v_mov_b64_e32 v[94:95], v[18:19]
	v_mov_b64_e32 v[102:103], v[18:19]
	v_mov_b64_e32 v[110:111], v[18:19]
	v_mov_b64_e32 v[118:119], v[18:19]
	v_mov_b64_e32 v[126:127], v[18:19]
	v_mov_b64_e32 v[134:135], v[18:19]
	v_mov_b64_e32 v[142:143], v[18:19]
	v_mov_b64_e32 v[218:219], v[0:1]
	s_waitcnt lgkmcnt(0)
	s_barrier
	s_branch .LBB0_595
; #define LAS __attribute__((address_space(3)))
; __device__ __forceinline__ f32x4 mma16(bf16x8 a, bf16x8 b, f32x4 c) { return __builtin_amdgcn_mfma_f32_16x16x32_bf16(a, b, c, 0, 0, 0); }
; __device__ __forceinline__ void attn_phase(LAS unsigned char* lds, const bf16_t* proj, bf16_t* oa, const float* lamp, const float* subg, const float* relb, const float* qg, int wg, int tid) {
;     ...
;         for (int kt = 0; kt < nkt; ++kt) {
;             const int cur = kt & 1, k0 = kt * 32; const bool more = kt + 1 < nkt;
;             u32x4 kr[2], vr[2];
;             if (more) {
; #pragma unroll
;                 for (int i = 0; i < 2; ++i) { const int id = tid + 512 * i, s = id >> 9, row = (id >> 4) & 31, ch = id & 15; kr[i] = *(const u32x4*)(ksrc + (size_t)(k0 + 32 + row) * DIFF_IN + s * 128 + ch * 8); }
; #pragma unroll
;                 for (int i = 0; i < 2; ++i) { const int id = tid + 512 * i, row = id >> 5, ch = id & 31; vr[i] = *(const u32x4*)(vsrc + (size_t)(k0 + 32 + row) * DIFF_IN + ch * 8); }
;             }
;             if (k0 <= qw0 + 15) {
;                 const LAS bf16_t* Kc = Kb + cur * KB_BUF; const LAS bf16_t* Vc = Vb + cur * VB_BUF;
;                 const bool far = (qw0 - (k0 + 31)) >= 128;
;                 f32x4 st[2][2];
;                 int qoff = (fr * KP + 8 * fq); asm volatile("" : "+v"(qoff));
; #pragma unroll
;                 for (int s = 0; s < 2; ++s) { const float ini = far ? (s ? c31b : c31a) : 0.f;
;                     st[s][0] = (f32x4){ini, ini, ini, ini}; st[s][1] = st[s][0];
; #pragma unroll
;                     for (int ks = 0; ks < 4; ++ks) { const bf16x8 qfr = *(const LAS bf16x8*)(Qw + s * 16 * KP + qoff + 32 * ks);
; #pragma unroll
;                         for (int T = 0; T < 2; ++T) st[s][T] = mma16(frag_rowk(Kc + s * 32 * KP, KP, 16 * T, 32 * ks, fr, fq), qfr, st[s][T]); } }
.LBB0_594:
	s_add_i32 s33, s33, 1
	s_sub_i32 s36, s36, 32
	s_add_u32 s100, s100, s8
	s_addc_u32 s101, s101, s9
	s_add_i32 s37, s37, 32
	s_and_b64 vcc, exec, s[0:1]
	s_waitcnt lgkmcnt(0)
	s_barrier
	s_cbranch_vccnz .LBB0_587
.LBB0_595:
	s_cmp_lt_u32 s33, s34
	s_cselect_b64 s[20:21], -1, 0
	s_cmp_ge_u32 s33, s34
	s_cselect_b64 s[0:1], -1, 0
	s_add_i32 s30, s33, -1
	s_and_b32 s46, s30, 1
	s_cmp_gt_i32 s37, s35
	s_cbranch_scc0 .Lat_compute
	s_andn2_b64 vcc, exec, s[20:21]
	s_cbranch_vccnz .LBB0_594
	v_lshl_add_u64 v[2:3], v[212:213], 0, s[100:101]
	v_lshl_add_u64 v[6:7], v[210:211], 0, s[100:101]
	v_lshl_add_u64 v[10:11], v[214:215], 0, s[100:101]
	v_lshl_add_u64 v[14:15], v[216:217], 0, s[100:101]
	global_load_dwordx4 v[2:5], v[2:3], off
	s_nop 0
	global_load_dwordx4 v[6:9], v[6:7], off
	s_nop 0
	global_load_dwordx4 v[10:13], v[10:11], off
	s_nop 0
	global_load_dwordx4 v[14:17], v[14:15], off
	s_branch .LBB0_634
.Lat_compute:
	v_lshl_add_u32 v0, v236, 1, s44
	s_mul_i32 s30, s46, 0x4800
	v_add_u32_e32 v224, s30, v245
	ds_read_b128 v[2:5], v0
	ds_read_b128 v[6:9], v224
	ds_read_b128 v[10:13], v224 offset:4608
	ds_read_b128 v[14:17], v0 offset:64
	ds_read_b128 v[162:165], v224 offset:64
	ds_read_b128 v[220:223], v224 offset:4672
	s_cmpk_gt_i32 s36, 0x7f
	s_cselect_b64 vcc, -1, 0
	v_cndmask_b32_e32 v228, 0, v243, vcc
	v_mov_b32_e32 v229, v228
	v_mov_b32_e32 v230, v228
	v_mov_b32_e32 v231, v228
	s_waitcnt lgkmcnt(3)
	s_nop 1
	v_mfma_f32_16x16x32_bf16 v[146:149], v[6:9], v[2:5], v[228:231]
	v_mfma_f32_16x16x32_bf16 v[150:153], v[10:13], v[2:5], v[228:231]
	ds_read_b128 v[2:5], v0 offset:128
	ds_read_b128 v[6:9], v224 offset:128
	ds_read_b128 v[10:13], v224 offset:4736
	s_waitcnt lgkmcnt(3)
	v_mfma_f32_16x16x32_bf16 v[146:149], v[162:165], v[14:17], v[146:149]
	v_mfma_f32_16x16x32_bf16 v[150:153], v[220:223], v[14:17], v[150:153]
	ds_read_b128 v[14:17], v0 offset:192
	ds_read_b128 v[162:165], v224 offset:192
	ds_read_b128 v[220:223], v224 offset:4800
	s_waitcnt lgkmcnt(3)
	v_mfma_f32_16x16x32_bf16 v[146:149], v[6:9], v[2:5], v[146:149]
	v_mfma_f32_16x16x32_bf16 v[150:153], v[10:13], v[2:5], v[150:153]
	ds_read_b128 v[2:5], v0 offset:4608
	ds_read_b128 v[6:9], v224 offset:9216
	ds_read_b128 v[10:13], v224 offset:13824
	s_waitcnt lgkmcnt(3)
	v_mfma_f32_16x16x32_bf16 v[146:149], v[162:165], v[14:17], v[146:149]
	v_mfma_f32_16x16x32_bf16 v[150:153], v[220:223], v[14:17], v[150:153]
	ds_read_b128 v[14:17], v0 offset:4672
	ds_read_b128 v[162:165], v224 offset:9280
	ds_read_b128 v[220:223], v224 offset:13888
	v_cndmask_b32_e32 v228, 0, v244, vcc
	v_mov_b32_e32 v229, v228
	v_mov_b32_e32 v230, v228
	v_mov_b32_e32 v231, v228
	s_waitcnt lgkmcnt(3)
	s_nop 1
	v_mfma_f32_16x16x32_bf16 v[158:161], v[6:9], v[2:5], v[228:231]
	v_mfma_f32_16x16x32_bf16 v[154:157], v[10:13], v[2:5], v[228:231]
	ds_read_b128 v[2:5], v0 offset:4736
	ds_read_b128 v[6:9], v224 offset:9344
	ds_read_b128 v[10:13], v224 offset:13952
	s_waitcnt lgkmcnt(3)
	v_mfma_f32_16x16x32_bf16 v[158:161], v[162:165], v[14:17], v[158:161]
	v_mfma_f32_16x16x32_bf16 v[154:157], v[220:223], v[14:17], v[154:157]
	ds_read_b128 v[14:17], v0 offset:4800
	ds_read_b128 v[162:165], v224 offset:9408
	ds_read_b128 v[220:223], v224 offset:14016
	s_waitcnt lgkmcnt(3)
	v_mfma_f32_16x16x32_bf16 v[158:161], v[6:9], v[2:5], v[158:161]
	v_mfma_f32_16x16x32_bf16 v[154:157], v[10:13], v[2:5], v[154:157]
	s_waitcnt lgkmcnt(0)
	v_mfma_f32_16x16x32_bf16 v[158:161], v[162:165], v[14:17], v[158:161]
	v_mfma_f32_16x16x32_bf16 v[154:157], v[220:223], v[14:17], v[154:157]
	s_and_b64 s[98:99], s[20:21], exec
	s_cbranch_scc0 .Lat_noload
	v_lshl_add_u64 v[2:3], v[212:213], 0, s[100:101]
	v_lshl_add_u64 v[6:7], v[210:211], 0, s[100:101]
	v_lshl_add_u64 v[10:11], v[214:215], 0, s[100:101]
	v_lshl_add_u64 v[14:15], v[216:217], 0, s[100:101]
	global_load_dwordx4 v[2:5], v[2:3], off
	s_nop 0
	global_load_dwordx4 v[6:9], v[6:7], off
	s_nop 0
	global_load_dwordx4 v[10:13], v[10:11], off
	s_nop 0
	global_load_dwordx4 v[14:17], v[14:15], off

; #define LAS __attribute__((address_space(3)))
; __device__ __forceinline__ unsigned cvtpk(float lo, float hi) { return pg8::cvt_pk_bf16(lo, hi); }
; __device__ __forceinline__ f32x4 mma16(bf16x8 a, bf16x8 b, f32x4 c) { return __builtin_amdgcn_mfma_f32_16x16x32_bf16(a, b, c, 0, 0, 0); }
; __device__ __forceinline__ void attn_phase(LAS unsigned char* lds, const bf16_t* proj, bf16_t* oa, const float* lamp, const float* subg, const float* relb, const float* qg, int wg, int tid) {
;     ...
;                 bf16x8 pf[2];
; #pragma unroll
;                 for (int s = 0; s < 2; ++s) { float ps = 0.f;
; #pragma unroll
;                     for (int T = 0; T < 2; ++T)
; #pragma unroll
;                         for (int r = 0; r < 4; ++r) { const float p = __builtin_amdgcn_exp2f(st[s][T][r]); st[s][T][r] = p; ps += p; }
;                     if (s == 0) l0 += ps; else l1 += ps;
;                     u32x4 w; w.x = cvtpk(st[s][0][0], st[s][0][1]); w.y = cvtpk(st[s][0][2], st[s][0][3]); w.z = cvtpk(st[s][1][0], st[s][1][1]); w.w = cvtpk(st[s][1][2], st[s][1][3]);
;                     pf[s] = __builtin_bit_cast(bf16x8, w); }
; #pragma unroll
;                 for (int vt = 0; vt < 16; ++vt) { const bf16x8 vf = frag_tr2(Vc, VP, 4 * fq, 16 + 4 * fq, 16 * vt, fr);
;                     o[0][vt] = mma16(vf, pf[0], o[0][vt]); o[1][vt] = mma16(vf, pf[1], o[1][vt]); }
;             }
;             if (more) {
;                 LAS bf16_t* Kn = Kb + (cur ^ 1) * KB_BUF; LAS bf16_t* Vn = Vb + (cur ^ 1) * VB_BUF;
; #pragma unroll
;                 for (int i = 0; i < 2; ++i) { const int id = tid + 512 * i, s = id >> 9, row = (id >> 4) & 31, ch = id & 15; *(LAS u32x4*)(Kn + (s * 32 + row) * KP + ch * 8) = kr[i]; }
; #pragma unroll
;                 for (int i = 0; i < 2; ++i) { const int id = tid + 512 * i, row = id >> 5, ch = id & 31; *(LAS u32x4*)(Vn + row * VP + ch * 8) = vr[i]; }
;             }
.LBB0_633:
	s_mul_i32 s30, s46, 0x4400
	v_add_u32_e32 v0, s30, v246
	v_exp_f32_e32 v231, v146
	v_exp_f32_e32 v229, v147
	v_exp_f32_e32 v227, v148
	v_exp_f32_e32 v225, v149
	v_exp_f32_e32 v223, v150
	v_exp_f32_e32 v221, v151
	v_exp_f32_e32 v165, v152
	v_exp_f32_e32 v163, v153
	v_exp_f32_e32 v230, v158
	v_exp_f32_e32 v228, v159
	v_exp_f32_e32 v226, v160
	v_exp_f32_e32 v224, v161
	v_exp_f32_e32 v222, v154
	v_exp_f32_e32 v220, v155
	v_exp_f32_e32 v164, v156
	v_exp_f32_e32 v162, v157
	ds_read_b64_tr_b16 v[158:159], v0 offset:36864
	ds_read_b64_tr_b16 v[160:161], v0 offset:45568
	ds_read_b64_tr_b16 v[154:155], v0 offset:36896
	ds_read_b64_tr_b16 v[156:157], v0 offset:45600
	v_cvt_pk_bf16_f32 v146, v231, v229
	v_cvt_pk_bf16_f32 v147, v227, v225
	v_cvt_pk_bf16_f32 v148, v223, v221
	v_cvt_pk_bf16_f32 v149, v165, v163
	v_cvt_pk_bf16_f32 v150, v230, v228
	v_cvt_pk_bf16_f32 v151, v226, v224
	v_cvt_pk_bf16_f32 v152, v222, v220
	v_cvt_pk_bf16_f32 v153, v164, v162
	v_pk_add_f32 v[228:229], v[228:229], v[230:231]
	v_pk_add_f32 v[226:227], v[226:227], v[228:229]
	v_add_f32_e64 v226, v224, v226
	v_add_f32_e64 v227, v225, v227
	v_pk_add_f32 v[226:227], v[222:223], v[226:227]
	v_add_f32_e64 v226, v220, v226
	v_add_f32_e64 v227, v221, v227
	v_pk_add_f32 v[226:227], v[164:165], v[226:227]
	v_add_f32_e64 v226, v162, v226
	v_add_f32_e64 v227, v163, v227
	v_pk_add_f32 v[218:219], v[218:219], v[226:227]
	ds_read_b64_tr_b16 v[162:163], v0 offset:36928
	ds_read_b64_tr_b16 v[164:165], v0 offset:45632
	ds_read_b64_tr_b16 v[220:221], v0 offset:36960
	ds_read_b64_tr_b16 v[222:223], v0 offset:45664
	ds_read_b64_tr_b16 v[224:225], v0 offset:36992
	ds_read_b64_tr_b16 v[226:227], v0 offset:45696
	ds_read_b64_tr_b16 v[228:229], v0 offset:37024
	ds_read_b64_tr_b16 v[230:231], v0 offset:45728
	s_waitcnt lgkmcnt(10)
	v_mfma_f32_16x16x32_bf16 v[142:145], v[158:161], v[146:149], v[142:145]
	v_mfma_f32_16x16x32_bf16 v[138:141], v[158:161], v[150:153], v[138:141]
	ds_read_b64_tr_b16 v[158:159], v0 offset:37056
	ds_read_b64_tr_b16 v[160:161], v0 offset:45760
	s_waitcnt lgkmcnt(10)
	v_mfma_f32_16x16x32_bf16 v[134:137], v[154:157], v[146:149], v[134:137]
	v_mfma_f32_16x16x32_bf16 v[130:133], v[154:157], v[150:153], v[130:133]
	ds_read_b64_tr_b16 v[154:155], v0 offset:37088
	ds_read_b64_tr_b16 v[156:157], v0 offset:45792
	s_waitcnt lgkmcnt(10)
	v_mfma_f32_16x16x32_bf16 v[126:129], v[162:165], v[146:149], v[126:129]
	v_mfma_f32_16x16x32_bf16 v[122:125], v[162:165], v[150:153], v[122:125]
	ds_read_b64_tr_b16 v[162:163], v0 offset:37120
	ds_read_b64_tr_b16 v[164:165], v0 offset:45824
	s_waitcnt lgkmcnt(10)
	v_mfma_f32_16x16x32_bf16 v[118:121], v[220:223], v[146:149], v[118:121]
	v_mfma_f32_16x16x32_bf16 v[114:117], v[220:223], v[150:153], v[114:117]
	ds_read_b64_tr_b16 v[220:221], v0 offset:37152
	ds_read_b64_tr_b16 v[222:223], v0 offset:45856
	s_waitcnt lgkmcnt(10)
	v_mfma_f32_16x16x32_bf16 v[110:113], v[224:227], v[146:149], v[110:113]
	v_mfma_f32_16x16x32_bf16 v[106:109], v[224:227], v[150:153], v[106:109]
	ds_read_b64_tr_b16 v[224:225], v0 offset:37184
	ds_read_b64_tr_b16 v[226:227], v0 offset:45888
	s_waitcnt lgkmcnt(10)
	v_mfma_f32_16x16x32_bf16 v[102:105], v[228:231], v[146:149], v[102:105]
	v_mfma_f32_16x16x32_bf16 v[98:101], v[228:231], v[150:153], v[98:101]
	ds_read_b64_tr_b16 v[228:229], v0 offset:37216
	ds_read_b64_tr_b16 v[230:231], v0 offset:45920
	s_waitcnt lgkmcnt(10)
	v_mfma_f32_16x16x32_bf16 v[94:97], v[158:161], v[146:149], v[94:97]
	v_mfma_f32_16x16x32_bf16 v[90:93], v[158:161], v[150:153], v[90:93]
	ds_read_b64_tr_b16 v[158:159], v0 offset:37248
	ds_read_b64_tr_b16 v[160:161], v0 offset:45952
	s_waitcnt lgkmcnt(10)
	v_mfma_f32_16x16x32_bf16 v[86:89], v[154:157], v[146:149], v[86:89]
	v_mfma_f32_16x16x32_bf16 v[82:85], v[154:157], v[150:153], v[82:85]
	ds_read_b64_tr_b16 v[154:155], v0 offset:37280
	ds_read_b64_tr_b16 v[156:157], v0 offset:45984
	s_waitcnt lgkmcnt(10)
	v_mfma_f32_16x16x32_bf16 v[78:81], v[162:165], v[146:149], v[78:81]
	v_mfma_f32_16x16x32_bf16 v[74:77], v[162:165], v[150:153], v[74:77]
	ds_read_b64_tr_b16 v[162:163], v0 offset:37312
	ds_read_b64_tr_b16 v[164:165], v0 offset:46016
	s_waitcnt lgkmcnt(10)
	v_mfma_f32_16x16x32_bf16 v[70:73], v[220:223], v[146:149], v[70:73]
	v_mfma_f32_16x16x32_bf16 v[66:69], v[220:223], v[150:153], v[66:69]
	ds_read_b64_tr_b16 v[220:221], v0 offset:37344
	ds_read_b64_tr_b16 v[222:223], v0 offset:46048
	s_waitcnt lgkmcnt(10)
	v_mfma_f32_16x16x32_bf16 v[62:65], v[224:227], v[146:149], v[62:65]
	v_mfma_f32_16x16x32_bf16 v[58:61], v[224:227], v[150:153], v[58:61]
	s_waitcnt lgkmcnt(8)
	v_mfma_f32_16x16x32_bf16 v[54:57], v[228:231], v[146:149], v[54:57]
	v_mfma_f32_16x16x32_bf16 v[50:53], v[228:231], v[150:153], v[50:53]
	s_andn2_b64 vcc, exec, s[20:21]
	s_cbranch_vccnz .Lat_nostage
	s_xor_b32 s30, s46, 1
	s_mul_i32 s31, s30, 0x4800
	v_add_u32_e32 v224, s31, v234
	v_add_u32_e32 v225, v224, v239
	v_add_u32_e32 v224, v224, v240
	s_mulk_i32 s30, 0x4400
	s_waitcnt vmcnt(3)
	ds_write_b128 v225, v[2:5]
	s_waitcnt vmcnt(2)
	ds_write_b128 v224, v[6:9]
	v_add_u32_e32 v224, s30, v235
	v_add_u32_e32 v225, v224, v237
	v_add_u32_e32 v224, v224, v238
	s_waitcnt vmcnt(1)
	ds_write_b128 v225, v[10:13] offset:36864
	s_waitcnt vmcnt(0)
	ds_write_b128 v224, v[14:17] offset:36864
.Lat_nostage:
	s_waitcnt lgkmcnt(6)
	v_mfma_f32_16x16x32_bf16 v[46:49], v[158:161], v[146:149], v[46:49]
	v_mfma_f32_16x16x32_bf16 v[42:45], v[158:161], v[150:153], v[42:45]
	s_waitcnt lgkmcnt(4)
	v_mfma_f32_16x16x32_bf16 v[38:41], v[154:157], v[146:149], v[38:41]
	v_mfma_f32_16x16x32_bf16 v[30:33], v[154:157], v[150:153], v[30:33]
	s_waitcnt lgkmcnt(2)
	v_mfma_f32_16x16x32_bf16 v[34:37], v[162:165], v[146:149], v[34:37]
	v_mfma_f32_16x16x32_bf16 v[22:25], v[162:165], v[150:153], v[22:25]
	s_waitcnt lgkmcnt(0)
	v_mfma_f32_16x16x32_bf16 v[26:29], v[220:223], v[146:149], v[26:29]
	v_mfma_f32_16x16x32_bf16 v[18:21], v[220:223], v[150:153], v[18:21]
	s_branch .LBB0_594

; #define LAS __attribute__((address_space(3)))
; __device__ __forceinline__ f32x4 mma16(bf16x8 a, bf16x8 b, f32x4 c) { return __builtin_amdgcn_mfma_f32_16x16x32_bf16(a, b, c, 0, 0, 0); }
; __device__ __forceinline__ void gla_pre_phase(LAS unsigned char* lds, const bf16_t* proj, const bf16_t* hn, const bf16_t* wlr, const float* wa2, const float* ba, bf16_t* QT, bf16_t* KT, bf16_t* KH, float* DEC, int wg, int nwg, int tid) {
;     ...
;           const int tt = wave & 3, kh = wave >> 2;
;           const bf16_t* ap = hn + (t0 + 16 * tt + fr) * DM + kh * 1024 + 8 * fq;
;           const bf16_t* bp = wlr + (size_t)fr * DM + kh * 1024 + 8 * fq;
;           f32x4 acc = (f32x4){0.f, 0.f, 0.f, 0.f};
; #pragma unroll 8
;           for (int ks = 0; ks < 32; ++ks) acc = mma16(*(const bf16x8*)(ap + 32 * ks), *(const bf16x8*)(bp + 32 * ks), acc);
;           if (kh == 1) *(LAS f32x4*)(part + (tt * 64 + lane) * 4) = acc;
.LBB0_659:
	v_mov_b32_e32 v2, 0
	s_mov_b64 s[62:63], 0
	v_mov_b32_e32 v3, v2
	v_mov_b64_e32 v[4:5], v[2:3]
	global_load_dwordx4 v[198:201], v[26:27], off offset:-256
	global_load_dwordx4 v[202:205], v[24:25], off offset:-256
	global_load_dwordx4 v[206:209], v[26:27], off offset:-192
	global_load_dwordx4 v[210:213], v[24:25], off offset:-192
	global_load_dwordx4 v[214:217], v[26:27], off offset:-128
	global_load_dwordx4 v[218:221], v[24:25], off offset:-128
	global_load_dwordx4 v[222:225], v[26:27], off offset:-64
	global_load_dwordx4 v[226:229], v[24:25], off offset:-64
	global_load_dwordx4 v[230:233], v[26:27], off
	global_load_dwordx4 v[234:237], v[24:25], off
	global_load_dwordx4 v[238:241], v[26:27], off offset:64
	global_load_dwordx4 v[242:245], v[24:25], off offset:64
	global_load_dwordx4 v[246:249], v[26:27], off offset:128
	global_load_dwordx4 v[114:117], v[24:25], off offset:128
	global_load_dwordx4 v[118:121], v[26:27], off offset:192
	global_load_dwordx4 v[122:125], v[24:25], off offset:192
	global_load_dwordx4 v[126:129], v[26:27], off offset:256
	global_load_dwordx4 v[130:133], v[24:25], off offset:256
	global_load_dwordx4 v[134:137], v[26:27], off offset:320
	global_load_dwordx4 v[138:141], v[24:25], off offset:320
	global_load_dwordx4 v[142:145], v[26:27], off offset:384
	global_load_dwordx4 v[146:149], v[24:25], off offset:384
	global_load_dwordx4 v[150:153], v[26:27], off offset:448
	global_load_dwordx4 v[154:157], v[24:25], off offset:448
	global_load_dwordx4 v[158:161], v[26:27], off offset:512
	global_load_dwordx4 v[162:165], v[24:25], off offset:512
	global_load_dwordx4 v[28:31], v[26:27], off offset:576
	global_load_dwordx4 v[32:35], v[24:25], off offset:576
	global_load_dwordx4 v[36:39], v[26:27], off offset:640
	global_load_dwordx4 v[40:43], v[24:25], off offset:640
	global_load_dwordx4 v[44:47], v[26:27], off offset:704
	global_load_dwordx4 v[48:51], v[24:25], off offset:704
	s_waitcnt vmcnt(30)
	v_mfma_f32_16x16x32_bf16 v[2:5], v[198:201], v[202:205], v[2:5]
	s_waitcnt vmcnt(28)
	v_mfma_f32_16x16x32_bf16 v[2:5], v[206:209], v[210:213], v[2:5]
	s_waitcnt vmcnt(26)
	v_mfma_f32_16x16x32_bf16 v[2:5], v[214:217], v[218:221], v[2:5]
	s_waitcnt vmcnt(24)
	v_mfma_f32_16x16x32_bf16 v[2:5], v[222:225], v[226:229], v[2:5]
	s_waitcnt vmcnt(22)
	v_mfma_f32_16x16x32_bf16 v[2:5], v[230:233], v[234:237], v[2:5]
	s_waitcnt vmcnt(20)
	v_mfma_f32_16x16x32_bf16 v[2:5], v[238:241], v[242:245], v[2:5]
	s_waitcnt vmcnt(18)
	v_mfma_f32_16x16x32_bf16 v[2:5], v[246:249], v[114:117], v[2:5]
	s_waitcnt vmcnt(16)
	v_mfma_f32_16x16x32_bf16 v[2:5], v[118:121], v[122:125], v[2:5]
	global_load_dwordx4 v[198:201], v[26:27], off offset:768
	global_load_dwordx4 v[202:205], v[24:25], off offset:768
	global_load_dwordx4 v[206:209], v[26:27], off offset:832
	global_load_dwordx4 v[210:213], v[24:25], off offset:832
	global_load_dwordx4 v[214:217], v[26:27], off offset:896
	global_load_dwordx4 v[218:221], v[24:25], off offset:896
	global_load_dwordx4 v[222:225], v[26:27], off offset:960
	global_load_dwordx4 v[226:229], v[24:25], off offset:960
	global_load_dwordx4 v[230:233], v[26:27], off offset:1024
	global_load_dwordx4 v[234:237], v[24:25], off offset:1024
	global_load_dwordx4 v[238:241], v[26:27], off offset:1088
	global_load_dwordx4 v[242:245], v[24:25], off offset:1088
	global_load_dwordx4 v[246:249], v[26:27], off offset:1152
	global_load_dwordx4 v[114:117], v[24:25], off offset:1152
	global_load_dwordx4 v[118:121], v[26:27], off offset:1216
	global_load_dwordx4 v[122:125], v[24:25], off offset:1216
	s_waitcnt vmcnt(30)
	v_mfma_f32_16x16x32_bf16 v[2:5], v[126:129], v[130:133], v[2:5]
	s_waitcnt vmcnt(28)
	v_mfma_f32_16x16x32_bf16 v[2:5], v[134:137], v[138:141], v[2:5]
	s_waitcnt vmcnt(26)
	v_mfma_f32_16x16x32_bf16 v[2:5], v[142:145], v[146:149], v[2:5]
	s_waitcnt vmcnt(24)
	v_mfma_f32_16x16x32_bf16 v[2:5], v[150:153], v[154:157], v[2:5]
	s_waitcnt vmcnt(22)
	v_mfma_f32_16x16x32_bf16 v[2:5], v[158:161], v[162:165], v[2:5]
	s_waitcnt vmcnt(20)
	v_mfma_f32_16x16x32_bf16 v[2:5], v[28:31], v[32:35], v[2:5]
	s_waitcnt vmcnt(18)
	v_mfma_f32_16x16x32_bf16 v[2:5], v[36:39], v[40:43], v[2:5]
	s_waitcnt vmcnt(16)
	v_mfma_f32_16x16x32_bf16 v[2:5], v[44:47], v[48:51], v[2:5]
	global_load_dwordx4 v[126:129], v[26:27], off offset:1280
	global_load_dwordx4 v[130:133], v[24:25], off offset:1280
	global_load_dwordx4 v[134:137], v[26:27], off offset:1344
	global_load_dwordx4 v[138:141], v[24:25], off offset:1344
	global_load_dwordx4 v[142:145], v[26:27], off offset:1408
	global_load_dwordx4 v[146:149], v[24:25], off offset:1408
	global_load_dwordx4 v[150:153], v[26:27], off offset:1472
	global_load_dwordx4 v[154:157], v[24:25], off offset:1472
	global_load_dwordx4 v[158:161], v[26:27], off offset:1536
	global_load_dwordx4 v[162:165], v[24:25], off offset:1536
	global_load_dwordx4 v[28:31], v[26:27], off offset:1600
	global_load_dwordx4 v[32:35], v[24:25], off offset:1600
	global_load_dwordx4 v[36:39], v[26:27], off offset:1664
	global_load_dwordx4 v[40:43], v[24:25], off offset:1664
	global_load_dwordx4 v[44:47], v[26:27], off offset:1728
	global_load_dwordx4 v[48:51], v[24:25], off offset:1728
	s_waitcnt vmcnt(30)
	v_mfma_f32_16x16x32_bf16 v[2:5], v[198:201], v[202:205], v[2:5]
	s_waitcnt vmcnt(28)
	v_mfma_f32_16x16x32_bf16 v[2:5], v[206:209], v[210:213], v[2:5]
	s_waitcnt vmcnt(26)
	v_mfma_f32_16x16x32_bf16 v[2:5], v[214:217], v[218:221], v[2:5]
	s_waitcnt vmcnt(24)
	v_mfma_f32_16x16x32_bf16 v[2:5], v[222:225], v[226:229], v[2:5]
	s_waitcnt vmcnt(22)
	v_mfma_f32_16x16x32_bf16 v[2:5], v[230:233], v[234:237], v[2:5]
	s_waitcnt vmcnt(20)
	v_mfma_f32_16x16x32_bf16 v[2:5], v[238:241], v[242:245], v[2:5]
	s_waitcnt vmcnt(18)
	v_mfma_f32_16x16x32_bf16 v[2:5], v[246:249], v[114:117], v[2:5]
	s_waitcnt vmcnt(16)
	v_mfma_f32_16x16x32_bf16 v[2:5], v[118:121], v[122:125], v[2:5]
	s_waitcnt vmcnt(14)
	v_mfma_f32_16x16x32_bf16 v[2:5], v[126:129], v[130:133], v[2:5]
	s_waitcnt vmcnt(12)
	v_mfma_f32_16x16x32_bf16 v[2:5], v[134:137], v[138:141], v[2:5]
	s_waitcnt vmcnt(10)
	v_mfma_f32_16x16x32_bf16 v[2:5], v[142:145], v[146:149], v[2:5]
	s_waitcnt vmcnt(8)
	v_mfma_f32_16x16x32_bf16 v[2:5], v[150:153], v[154:157], v[2:5]
	s_waitcnt vmcnt(6)
	v_mfma_f32_16x16x32_bf16 v[2:5], v[158:161], v[162:165], v[2:5]
	s_waitcnt vmcnt(4)
	v_mfma_f32_16x16x32_bf16 v[2:5], v[28:31], v[32:35], v[2:5]
	s_waitcnt vmcnt(2)
	v_mfma_f32_16x16x32_bf16 v[2:5], v[36:39], v[40:43], v[2:5]
	s_waitcnt vmcnt(0)
	v_mfma_f32_16x16x32_bf16 v[2:5], v[44:47], v[48:51], v[2:5]
	s_mov_b64 s[62:63], 0x800
	s_nop 1
	s_and_b64 vcc, exec, s[54:55]
	s_cbranch_vccz .LBB0_663
	s_nop 4
	ds_write_b128 v68, v[2:5] offset:6144
